# rmsnorm loops software-pipelined by one row (next row's loads in flight during reduce/store) on top of stage-2 de-serialisation
# baseline (speedup 1.0000x reference)
; __device__ __forceinline__ u32x2 pack4(f32x4 v) { u32x2 r; r.x = cvt_pk_bf16(v[0], v[1]); r.y = cvt_pk_bf16(v[2], v[3]); return r; }
; __device__ __forceinline__ void rmsnorm_phase(const float* x, const float* g, bf16_t* outb, float* outf) {
;     ...
;     f32x4 gv[4];
; #pragma unroll
;     for (int i = 0; i < 4; ++i) gv[i] = *(const f32x4*)(g + (lane + i * 64) * 4);
;     for (int row = gw; row < T; row += nw) {
;         const float* xr = x + (size_t)row * D;
;         f32x4 v[4];
;         float ss = 0.f;
; #pragma unroll
;         for (int i = 0; i < 4; ++i) { v[i] = __builtin_nontemporal_load((const f32x4*)(xr + (lane + i * 64) * 4)); ss += v[i][0] * v[i][0] + v[i][1] * v[i][1] + v[i][2] * v[i][2] + v[i][3] * v[i][3]; }
; #pragma unroll
;         for (int o = 32; o >= 1; o >>= 1) ss += __shfl_xor(ss, o);
;         const float r = rsqrtf(ss * (1.0f / D) + EPS);
; #pragma unroll
;         for (int i = 0; i < 4; ++i) {
;             const f32x4 y = v[i] * r * gv[i];
;             if (outb) *(u32x2*)(outb + (size_t)row * D + (lane + i * 64) * 4) = pack4(y);
;             else __builtin_nontemporal_store(y, (f32x4*)(outf + (size_t)row * D + (lane + i * 64) * 4));
;         }
;     }
.LBB0_98:
	v_lshrrev_b32_e32 v116, 6, v114
	v_readlane_b32 s0, v245, 0
	v_and_b32_e32 v136, 0xfc, v0
	s_lshl_b32 s10, s58, 2
	v_lshl_add_u32 v112, s0, 2, v116
	s_mov_b32 s0, 0x8000
	v_ashrrev_i32_e32 v113, 31, v112
	v_lshlrev_b32_e32 v146, 2, v136
	v_mbcnt_lo_u32_b32 v138, -1, 0
	v_and_b32_e32 v115, 63, v114
	v_cmp_gt_i32_e64 s[2:3], s0, v112
	s_mov_b64 s[0:1], exec
	s_nop 0
	v_writelane_b32 v245, s2, 49
	s_nop 1
	v_writelane_b32 v245, s3, 50
	s_and_b64 s[2:3], s[0:1], s[2:3]
	s_mov_b64 exec, s[2:3]
	s_cbranch_execz .LBB0_101
	v_readlane_b32 s12, v245, 10
	v_readlane_b32 s13, v245, 11
	v_readlane_b32 s14, v245, 12
	v_readlane_b32 s15, v245, 13
	v_readlane_b32 s16, v245, 14
	v_readlane_b32 s17, v245, 15
	s_mov_b64 s[4:5], s[12:13]
	s_mov_b64 s[6:7], s[14:15]
	global_load_dwordx4 v[0:3], v146, s[6:7]
	global_load_dwordx4 v[4:7], v146, s[6:7] offset:1024
	global_load_dwordx4 v[8:11], v146, s[6:7] offset:2048
	global_load_dwordx4 v[12:15], v146, s[6:7] offset:3072
	v_mbcnt_hi_u32_b32 v16, -1, v138
	v_and_b32_e32 v17, 64, v16
	v_add_u32_e32 v17, 64, v17
	v_xor_b32_e32 v18, 32, v16
	v_cmp_lt_i32_e32 vcc, v18, v17
	s_mov_b64 s[8:9], s[16:17]
	s_mov_b64 s[2:3], 0x3800000
	v_cndmask_b32_e32 v18, v16, v18, vcc
	v_lshlrev_b32_e32 v20, 2, v18
	v_xor_b32_e32 v18, 16, v16
	v_cmp_lt_i32_e32 vcc, v18, v17
	s_ashr_i32 s11, s10, 31
	s_mov_b64 s[6:7], 0
	v_cndmask_b32_e32 v18, v16, v18, vcc
	v_lshlrev_b32_e32 v21, 2, v18
	v_xor_b32_e32 v18, 8, v16
	v_cmp_lt_i32_e32 vcc, v18, v17
	v_mov_b32_e32 v26, 0x358637bd
	s_mov_b32 s8, 0x800000
	v_cndmask_b32_e32 v18, v16, v18, vcc
	v_lshlrev_b32_e32 v22, 2, v18
	v_xor_b32_e32 v18, 4, v16
	v_cmp_lt_i32_e32 vcc, v18, v17
	s_movk_i32 s9, 0x7fff
	v_mov_b32_e32 v27, v112
	v_cndmask_b32_e32 v18, v16, v18, vcc
	v_lshlrev_b32_e32 v23, 2, v18
	v_xor_b32_e32 v18, 2, v16
	v_cmp_lt_i32_e32 vcc, v18, v17
	v_readlane_b32 s18, v245, 16
	v_readlane_b32 s19, v245, 17
	v_cndmask_b32_e32 v18, v16, v18, vcc
	v_lshlrev_b32_e32 v24, 2, v18
	v_xor_b32_e32 v18, 1, v16
	v_cmp_lt_i32_e32 vcc, v18, v17
	v_readlane_b32 s20, v245, 18
	v_readlane_b32 s21, v245, 19
	v_cndmask_b32_e32 v16, v16, v18, vcc
	v_lshlrev_b32_e32 v25, 2, v16
	v_lshlrev_b64 v[16:17], 11, v[112:113]
	v_lshlrev_b64 v[18:19], 12, v[112:113]
	v_lshl_or_b32 v16, v115, 3, v16
	v_lshl_or_b32 v18, v115, 4, v18
	v_lshl_add_u64 v[16:17], s[56:57], 0, v[16:17]
	v_lshl_add_u64 v[18:19], s[4:5], 0, v[18:19]
	s_mov_b64 s[4:5], 0xc00
	v_lshl_add_u64 v[16:17], v[16:17], 0, s[2:3]
	s_lshl_b64 s[2:3], s[10:11], 11
	v_lshl_add_u64 v[18:19], v[18:19], 0, s[4:5]
	s_lshl_b64 s[4:5], s[10:11], 12
	v_readlane_b32 s22, v245, 20
	v_readlane_b32 s23, v245, 21
	v_readlane_b32 s24, v245, 22
	v_readlane_b32 s25, v245, 23
	v_readlane_b32 s26, v245, 24
	v_readlane_b32 s27, v245, 25
	global_load_dwordx4 v[28:31], v[18:19], off offset:-3072 nt
	global_load_dwordx4 v[32:35], v[18:19], off offset:-2048 nt
	global_load_dwordx4 v[36:39], v[18:19], off offset:-1024 nt
	global_load_dwordx4 v[40:43], v[18:19], off nt
	v_lshl_add_u64 v[18:19], v[18:19], 0, s[4:5]
	s_waitcnt vmcnt(0)
.LBB0_100:
	v_add_u32_e32 v27, s10, v27
	v_cmp_lt_i32_e32 vcc, s9, v27
	s_or_b64 s[6:7], vcc, s[6:7]
	s_cbranch_vccnz .Lrp_skip_0
	global_load_dwordx4 v[180:183], v[18:19], off offset:-3072 nt
	global_load_dwordx4 v[184:187], v[18:19], off offset:-2048 nt
	global_load_dwordx4 v[188:191], v[18:19], off offset:-1024 nt
	global_load_dwordx4 v[192:195], v[18:19], off nt
	v_lshl_add_u64 v[18:19], v[18:19], 0, s[4:5]
.Lrp_skip_0:
	v_mov_b32_e32 v46, v29
	v_mov_b32_e32 v47, v33
	v_mov_b32_e32 v44, v28
	v_mov_b32_e32 v45, v32
	v_mov_b32_e32 v54, v37
	v_mov_b32_e32 v55, v41
	v_pk_mul_f32 v[46:47], v[46:47], v[46:47]
	v_mov_b32_e32 v48, v30
	v_mov_b32_e32 v49, v34
	v_mov_b32_e32 v52, v36
	v_mov_b32_e32 v53, v40
	v_pk_mul_f32 v[54:55], v[54:55], v[54:55]
	v_pk_fma_f32 v[44:45], v[44:45], v[44:45], v[46:47]
	v_mov_b32_e32 v50, v31
	v_mov_b32_e32 v51, v35
	v_mov_b32_e32 v56, v38
	v_mov_b32_e32 v57, v42
	v_pk_fma_f32 v[46:47], v[52:53], v[52:53], v[54:55]
	v_pk_fma_f32 v[44:45], v[48:49], v[48:49], v[44:45]
	v_mov_b32_e32 v58, v39
	v_mov_b32_e32 v59, v43
	v_pk_fma_f32 v[46:47], v[56:57], v[56:57], v[46:47]
	v_pk_fma_f32 v[44:45], v[50:51], v[50:51], v[44:45]
	v_pk_fma_f32 v[46:47], v[58:59], v[58:59], v[46:47]
	v_add_f32_e32 v44, v44, v45
	v_add_f32_e32 v44, v44, v46
	v_add_f32_e32 v44, v44, v47
	v_mov_b32_e32 v45, v44
	s_nop 1
	v_permlane32_swap_b32_e32 v44, v45
	v_add_f32_e32 v44, v44, v45
	v_mov_b32_e32 v45, v44
	s_nop 1
	v_permlane16_swap_b32_e32 v44, v45
	v_add_f32_e32 v44, v44, v45
	s_nop 1
	v_add_f32_dpp v44, v44, v44 row_ror:8 row_mask:0xf bank_mask:0xf
	s_nop 1
	v_add_f32_dpp v44, v44, v44 row_ror:4 row_mask:0xf bank_mask:0xf
	s_nop 1
	v_add_f32_dpp v44, v44, v44 quad_perm:[2,3,0,1] row_mask:0xf bank_mask:0xf
	s_nop 1
	v_add_f32_dpp v44, v44, v44 quad_perm:[1,0,3,2] row_mask:0xf bank_mask:0xf
	v_fmamk_f32 v44, v44, 0x3a800000, v26
	v_mul_f32_e32 v45, 0x4b800000, v44
	v_cmp_gt_f32_e32 vcc, s8, v44
	s_nop 1
	v_cndmask_b32_e32 v44, v44, v45, vcc
	v_rsq_f32_e32 v44, v44
	s_nop 0
	v_mul_f32_e32 v45, 0x45800000, v44
	v_cndmask_b32_e32 v44, v44, v45, vcc
	v_pk_mul_f32 v[28:29], v[28:29], v[44:45] op_sel_hi:[1,0]
	v_pk_mul_f32 v[30:31], v[30:31], v[44:45] op_sel_hi:[1,0]
	v_pk_mul_f32 v[32:33], v[32:33], v[44:45] op_sel_hi:[1,0]
	v_pk_mul_f32 v[34:35], v[34:35], v[44:45] op_sel_hi:[1,0]
	v_pk_mul_f32 v[36:37], v[36:37], v[44:45] op_sel_hi:[1,0]
	v_pk_mul_f32 v[38:39], v[38:39], v[44:45] op_sel_hi:[1,0]
	v_pk_mul_f32 v[40:41], v[40:41], v[44:45] op_sel_hi:[1,0]
	v_pk_mul_f32 v[42:43], v[42:43], v[44:45] op_sel_hi:[1,0]
	v_pk_mul_f32 v[30:31], v[2:3], v[30:31]
	v_pk_mul_f32 v[28:29], v[0:1], v[28:29]
	v_pk_mul_f32 v[34:35], v[6:7], v[34:35]
	v_pk_mul_f32 v[32:33], v[4:5], v[32:33]
	v_pk_mul_f32 v[38:39], v[10:11], v[38:39]
	v_pk_mul_f32 v[36:37], v[8:9], v[36:37]
	v_pk_mul_f32 v[42:43], v[14:15], v[42:43]
	v_pk_mul_f32 v[40:41], v[12:13], v[40:41]
	v_cvt_pk_bf16_f32 v28, v28, v29
	v_cvt_pk_bf16_f32 v29, v30, v31
	v_cvt_pk_bf16_f32 v30, v32, v33
	v_cvt_pk_bf16_f32 v31, v34, v35
	v_cvt_pk_bf16_f32 v32, v36, v37
	v_cvt_pk_bf16_f32 v33, v38, v39
	v_cvt_pk_bf16_f32 v34, v40, v41
	v_cvt_pk_bf16_f32 v35, v42, v43
	global_store_dwordx2 v[16:17], v[28:29], off
	global_store_dwordx2 v[16:17], v[30:31], off offset:512
	global_store_dwordx2 v[16:17], v[32:33], off offset:1024
	global_store_dwordx2 v[16:17], v[34:35], off offset:1536
	v_lshl_add_u64 v[16:17], v[16:17], 0, s[2:3]
	s_waitcnt vmcnt(4)
	v_mov_b32_e32 v28, v180
	v_mov_b32_e32 v29, v181
	v_mov_b32_e32 v30, v182
	v_mov_b32_e32 v31, v183
	v_mov_b32_e32 v32, v184
	v_mov_b32_e32 v33, v185
	v_mov_b32_e32 v34, v186
	v_mov_b32_e32 v35, v187
	v_mov_b32_e32 v36, v188
	v_mov_b32_e32 v37, v189
	v_mov_b32_e32 v38, v190
	v_mov_b32_e32 v39, v191
	v_mov_b32_e32 v40, v192
	v_mov_b32_e32 v41, v193
	v_mov_b32_e32 v42, v194
	v_mov_b32_e32 v43, v195
	s_andn2_b64 exec, exec, s[6:7]
	s_cbranch_execnz .LBB0_100

; __device__ __forceinline__ u32x2 pack4(f32x4 v) { u32x2 r; r.x = cvt_pk_bf16(v[0], v[1]); r.y = cvt_pk_bf16(v[2], v[3]); return r; }
; __device__ __forceinline__ void rmsnorm_phase(const float* x, const float* g, bf16_t* outb, float* outf) {
;     ...
;     f32x4 gv[4];
; #pragma unroll
;     for (int i = 0; i < 4; ++i) gv[i] = *(const f32x4*)(g + (lane + i * 64) * 4);
;     for (int row = gw; row < T; row += nw) {
;         const float* xr = x + (size_t)row * D;
;         f32x4 v[4];
;         float ss = 0.f;
; #pragma unroll
;         for (int i = 0; i < 4; ++i) { v[i] = __builtin_nontemporal_load((const f32x4*)(xr + (lane + i * 64) * 4)); ss += v[i][0] * v[i][0] + v[i][1] * v[i][1] + v[i][2] * v[i][2] + v[i][3] * v[i][3]; }
; #pragma unroll
;         for (int o = 32; o >= 1; o >>= 1) ss += __shfl_xor(ss, o);
;         const float r = rsqrtf(ss * (1.0f / D) + EPS);
; #pragma unroll
;         for (int i = 0; i < 4; ++i) {
;             const f32x4 y = v[i] * r * gv[i];
;             if (outb) *(u32x2*)(outb + (size_t)row * D + (lane + i * 64) * 4) = pack4(y);
;             else __builtin_nontemporal_store(y, (f32x4*)(outf + (size_t)row * D + (lane + i * 64) * 4));
;         }
;     }
.LBB0_508:
	s_or_b64 exec, exec, s[34:35]
	s_waitcnt lgkmcnt(0)
	s_barrier
	s_mov_b64 s[0:1], exec
	v_readlane_b32 s4, v245, 49
	v_readlane_b32 s5, v245, 50
	s_and_b64 s[4:5], s[0:1], s[4:5]
	v_readlane_b32 s40, v245, 51
	v_readlane_b32 s41, v245, 52
	s_mov_b64 exec, s[4:5]
	s_cbranch_execz .LBB0_511
	v_readlane_b32 s4, v245, 10
	v_readlane_b32 s8, v245, 14
	v_readlane_b32 s9, v245, 15
	s_nop 4
	global_load_dwordx4 v[0:3], v146, s[8:9]
	global_load_dwordx4 v[4:7], v146, s[8:9] offset:1024
	global_load_dwordx4 v[8:11], v146, s[8:9] offset:2048
	global_load_dwordx4 v[12:15], v146, s[8:9] offset:3072
	v_cmp_lt_i32_e32 vcc, v140, v138
	v_lshlrev_b64 v[18:19], 12, v[112:113]
	v_readlane_b32 s5, v245, 11
	v_cndmask_b32_e32 v16, v117, v140, vcc
	v_cmp_lt_i32_e32 vcc, v139, v138
	v_lshlrev_b32_e32 v20, 2, v16
	v_readlane_b32 s6, v245, 12
	v_cndmask_b32_e32 v16, v117, v139, vcc
	v_lshlrev_b32_e32 v21, 2, v16
	v_xor_b32_e32 v16, 8, v117
	v_cmp_lt_i32_e32 vcc, v16, v138
	v_readlane_b32 s7, v245, 13
	v_lshl_or_b32 v18, v115, 4, v18
	v_cndmask_b32_e32 v16, v117, v16, vcc
	v_lshlrev_b32_e32 v22, 2, v16
	v_xor_b32_e32 v16, 4, v117
	v_cmp_lt_i32_e32 vcc, v16, v138
	v_readlane_b32 s10, v245, 16
	v_readlane_b32 s11, v245, 17
	v_cndmask_b32_e32 v16, v117, v16, vcc
	v_lshlrev_b32_e32 v23, 2, v16
	v_xor_b32_e32 v16, 2, v117
	v_cmp_lt_i32_e32 vcc, v16, v138
	s_mov_b64 s[4:5], 0x3800000
	s_ashr_i32 s41, s40, 31
	v_cndmask_b32_e32 v16, v117, v16, vcc
	v_lshlrev_b32_e32 v24, 2, v16
	v_xor_b32_e32 v16, 1, v117
	v_cmp_lt_i32_e32 vcc, v16, v138
	v_lshl_add_u64 v[18:19], s[54:55], 0, v[18:19]
	s_mov_b64 s[6:7], 0xc00
	v_cndmask_b32_e32 v16, v117, v16, vcc
	v_lshlrev_b32_e32 v25, 2, v16
	v_lshlrev_b64 v[16:17], 11, v[112:113]
	v_lshl_or_b32 v16, v115, 3, v16
	v_lshl_add_u64 v[16:17], s[56:57], 0, v[16:17]
	v_lshl_add_u64 v[16:17], v[16:17], 0, s[4:5]
	s_lshl_b64 s[4:5], s[40:41], 11
	v_lshl_add_u64 v[18:19], v[18:19], 0, s[6:7]
	s_lshl_b64 s[6:7], s[40:41], 12
	s_mov_b64 s[8:9], 0
	v_mov_b32_e32 v26, 0x358637bd
	s_mov_b32 s10, 0x800000
	s_movk_i32 s11, 0x7fff
	v_mov_b32_e32 v27, v112
	v_readlane_b32 s12, v245, 18
	v_readlane_b32 s13, v245, 19
	v_readlane_b32 s14, v245, 20
	v_readlane_b32 s15, v245, 21
	v_readlane_b32 s16, v245, 22
	v_readlane_b32 s17, v245, 23
	v_readlane_b32 s18, v245, 24
	v_readlane_b32 s19, v245, 25
	global_load_dwordx4 v[28:31], v[18:19], off offset:-3072 nt
	global_load_dwordx4 v[32:35], v[18:19], off offset:-2048 nt
	global_load_dwordx4 v[36:39], v[18:19], off offset:-1024 nt
	global_load_dwordx4 v[40:43], v[18:19], off nt
	v_lshl_add_u64 v[18:19], v[18:19], 0, s[6:7]
	s_waitcnt vmcnt(0)
.LBB0_510:
	v_add_u32_e32 v27, s40, v27
	v_cmp_lt_i32_e32 vcc, s11, v27
	s_or_b64 s[8:9], vcc, s[8:9]
	s_cbranch_vccnz .Lrp_skip_1
	global_load_dwordx4 v[180:183], v[18:19], off offset:-3072 nt
	global_load_dwordx4 v[184:187], v[18:19], off offset:-2048 nt
	global_load_dwordx4 v[188:191], v[18:19], off offset:-1024 nt
	global_load_dwordx4 v[192:195], v[18:19], off nt
	v_lshl_add_u64 v[18:19], v[18:19], 0, s[6:7]
.Lrp_skip_1:
	v_mov_b32_e32 v46, v29
	v_mov_b32_e32 v47, v33
	v_mov_b32_e32 v44, v28
	v_mov_b32_e32 v45, v32
	v_mov_b32_e32 v54, v37
	v_mov_b32_e32 v55, v41
	v_pk_mul_f32 v[46:47], v[46:47], v[46:47]
	v_mov_b32_e32 v48, v30
	v_mov_b32_e32 v49, v34
	v_mov_b32_e32 v52, v36
	v_mov_b32_e32 v53, v40
	v_pk_mul_f32 v[54:55], v[54:55], v[54:55]
	v_pk_fma_f32 v[44:45], v[44:45], v[44:45], v[46:47]
	v_mov_b32_e32 v50, v31
	v_mov_b32_e32 v51, v35
	v_mov_b32_e32 v56, v38
	v_mov_b32_e32 v57, v42
	v_pk_fma_f32 v[46:47], v[52:53], v[52:53], v[54:55]
	v_pk_fma_f32 v[44:45], v[48:49], v[48:49], v[44:45]
	v_mov_b32_e32 v58, v39
	v_mov_b32_e32 v59, v43
	v_pk_fma_f32 v[46:47], v[56:57], v[56:57], v[46:47]
	v_pk_fma_f32 v[44:45], v[50:51], v[50:51], v[44:45]
	v_pk_fma_f32 v[46:47], v[58:59], v[58:59], v[46:47]
	v_add_f32_e32 v44, v44, v45
	v_add_f32_e32 v44, v44, v46
	v_add_f32_e32 v44, v44, v47
	v_mov_b32_e32 v45, v44
	s_nop 1
	v_permlane32_swap_b32_e32 v44, v45
	v_add_f32_e32 v44, v44, v45
	v_mov_b32_e32 v45, v44
	s_nop 1
	v_permlane16_swap_b32_e32 v44, v45
	v_add_f32_e32 v44, v44, v45
	s_nop 1
	v_add_f32_dpp v44, v44, v44 row_ror:8 row_mask:0xf bank_mask:0xf
	s_nop 1
	v_add_f32_dpp v44, v44, v44 row_ror:4 row_mask:0xf bank_mask:0xf
	s_nop 1
	v_add_f32_dpp v44, v44, v44 quad_perm:[2,3,0,1] row_mask:0xf bank_mask:0xf
	s_nop 1
	v_add_f32_dpp v44, v44, v44 quad_perm:[1,0,3,2] row_mask:0xf bank_mask:0xf
	v_fmamk_f32 v44, v44, 0x3a800000, v26
	v_mul_f32_e32 v45, 0x4b800000, v44
	v_cmp_gt_f32_e32 vcc, s10, v44
	s_nop 1
	v_cndmask_b32_e32 v44, v44, v45, vcc
	v_rsq_f32_e32 v44, v44
	s_nop 0
	v_mul_f32_e32 v45, 0x45800000, v44
	v_cndmask_b32_e32 v44, v44, v45, vcc
	v_pk_mul_f32 v[28:29], v[28:29], v[44:45] op_sel_hi:[1,0]
	v_pk_mul_f32 v[30:31], v[30:31], v[44:45] op_sel_hi:[1,0]
	v_pk_mul_f32 v[32:33], v[32:33], v[44:45] op_sel_hi:[1,0]
	v_pk_mul_f32 v[34:35], v[34:35], v[44:45] op_sel_hi:[1,0]
	v_pk_mul_f32 v[36:37], v[36:37], v[44:45] op_sel_hi:[1,0]
	v_pk_mul_f32 v[38:39], v[38:39], v[44:45] op_sel_hi:[1,0]
	v_pk_mul_f32 v[40:41], v[40:41], v[44:45] op_sel_hi:[1,0]
	v_pk_mul_f32 v[42:43], v[42:43], v[44:45] op_sel_hi:[1,0]
	v_pk_mul_f32 v[30:31], v[2:3], v[30:31]
	v_pk_mul_f32 v[28:29], v[0:1], v[28:29]
	v_pk_mul_f32 v[34:35], v[6:7], v[34:35]
	v_pk_mul_f32 v[32:33], v[4:5], v[32:33]
	v_pk_mul_f32 v[38:39], v[10:11], v[38:39]
	v_pk_mul_f32 v[36:37], v[8:9], v[36:37]
	v_pk_mul_f32 v[42:43], v[14:15], v[42:43]
	v_pk_mul_f32 v[40:41], v[12:13], v[40:41]
	v_cvt_pk_bf16_f32 v28, v28, v29
	v_cvt_pk_bf16_f32 v29, v30, v31
	v_cvt_pk_bf16_f32 v30, v32, v33
	v_cvt_pk_bf16_f32 v31, v34, v35
	v_cvt_pk_bf16_f32 v32, v36, v37
	v_cvt_pk_bf16_f32 v33, v38, v39
	v_cvt_pk_bf16_f32 v34, v40, v41
	v_cvt_pk_bf16_f32 v35, v42, v43
	global_store_dwordx2 v[16:17], v[28:29], off
	global_store_dwordx2 v[16:17], v[30:31], off offset:512
	global_store_dwordx2 v[16:17], v[32:33], off offset:1024
	global_store_dwordx2 v[16:17], v[34:35], off offset:1536
	v_lshl_add_u64 v[16:17], v[16:17], 0, s[4:5]
	s_waitcnt vmcnt(4)
	v_mov_b32_e32 v28, v180
	v_mov_b32_e32 v29, v181
	v_mov_b32_e32 v30, v182
	v_mov_b32_e32 v31, v183
	v_mov_b32_e32 v32, v184
	v_mov_b32_e32 v33, v185
	v_mov_b32_e32 v34, v186
	v_mov_b32_e32 v35, v187
	v_mov_b32_e32 v36, v188
	v_mov_b32_e32 v37, v189
	v_mov_b32_e32 v38, v190
	v_mov_b32_e32 v39, v191
	v_mov_b32_e32 v40, v192
	v_mov_b32_e32 v41, v193
	v_mov_b32_e32 v42, v194
	v_mov_b32_e32 v43, v195
	s_andn2_b64 exec, exec, s[8:9]
	s_cbranch_execnz .LBB0_510

; __device__ __forceinline__ void rmsnorm_phase(const float* x, const float* g, bf16_t* outb, float* outf) {
;     ...
;     f32x4 gv[4];
; #pragma unroll
;     for (int i = 0; i < 4; ++i) gv[i] = *(const f32x4*)(g + (lane + i * 64) * 4);
;     for (int row = gw; row < T; row += nw) {
;         const float* xr = x + (size_t)row * D;
;         f32x4 v[4];
;         float ss = 0.f;
; #pragma unroll
;         for (int i = 0; i < 4; ++i) { v[i] = __builtin_nontemporal_load((const f32x4*)(xr + (lane + i * 64) * 4)); ss += v[i][0] * v[i][0] + v[i][1] * v[i][1] + v[i][2] * v[i][2] + v[i][3] * v[i][3]; }
.LBB0_667:
	s_or_b64 exec, exec, s[2:3]
	v_or_b32_e32 v0, 0x100, v136
	v_or_b32_e32 v1, 0x200, v136
	v_or_b32_e32 v2, 0x300, v136
	v_lshlrev_b32_e32 v168, 2, v0
	v_lshlrev_b32_e32 v167, 2, v1
	v_lshlrev_b32_e32 v169, 2, v2
	s_waitcnt lgkmcnt(0)
	s_barrier
	s_mov_b64 s[0:1], exec
	v_readlane_b32 s2, v245, 49
	v_readlane_b32 s3, v245, 50
	s_and_b64 s[2:3], s[0:1], s[2:3]
	s_mov_b64 exec, s[2:3]
	s_cbranch_execz .LBB0_670
	v_readlane_b32 s8, v245, 10
	v_readlane_b32 s10, v245, 12
	v_readlane_b32 s11, v245, 13
	s_mov_b64 s[6:7], s[10:11]
	s_add_u32 s2, s6, 0x1000
	s_addc_u32 s3, s7, 0
	global_load_dwordx4 v[0:3], v168, s[2:3]
	global_load_dwordx4 v[4:7], v167, s[2:3]
	global_load_dwordx4 v[8:11], v146, s[2:3]
	global_load_dwordx4 v[12:15], v169, s[2:3]
	v_cmp_lt_i32_e32 vcc, v140, v138
	v_lshlrev_b64 v[18:19], 12, v[112:113]
	v_lshl_or_b32 v18, v115, 4, v18
	v_cndmask_b32_e32 v16, v117, v140, vcc
	v_cmp_lt_i32_e32 vcc, v139, v138
	v_lshlrev_b32_e32 v20, 2, v16
	v_readlane_b32 s9, v245, 11
	v_cndmask_b32_e32 v16, v117, v139, vcc
	v_lshlrev_b32_e32 v21, 2, v16
	v_xor_b32_e32 v16, 8, v117
	v_cmp_lt_i32_e32 vcc, v16, v138
	s_mov_b64 s[2:3], 0x3800000
	s_ashr_i32 s41, s40, 31
	v_cndmask_b32_e32 v16, v117, v16, vcc
	v_lshlrev_b32_e32 v22, 2, v16
	v_xor_b32_e32 v16, 4, v117
	v_cmp_lt_i32_e32 vcc, v16, v138
	v_lshl_add_u64 v[18:19], s[54:55], 0, v[18:19]
	s_mov_b64 s[6:7], 0xc00
	v_cndmask_b32_e32 v16, v117, v16, vcc
	v_lshlrev_b32_e32 v23, 2, v16
	v_xor_b32_e32 v16, 2, v117
	v_cmp_lt_i32_e32 vcc, v16, v138
	v_lshl_add_u64 v[18:19], v[18:19], 0, s[6:7]
	s_lshl_b64 s[6:7], s[40:41], 12
	v_cndmask_b32_e32 v16, v117, v16, vcc
	v_lshlrev_b32_e32 v24, 2, v16
	v_xor_b32_e32 v16, 1, v117
	v_cmp_lt_i32_e32 vcc, v16, v138
	s_mov_b64 s[8:9], 0
	v_mov_b32_e32 v26, 0x358637bd
	v_cndmask_b32_e32 v16, v117, v16, vcc
	v_lshlrev_b32_e32 v25, 2, v16
	v_lshlrev_b64 v[16:17], 11, v[112:113]
	v_lshl_or_b32 v16, v115, 3, v16
	v_lshl_add_u64 v[16:17], s[56:57], 0, v[16:17]
	v_lshl_add_u64 v[16:17], v[16:17], 0, s[2:3]
	s_lshl_b64 s[2:3], s[40:41], 11
	s_mov_b32 s10, 0x800000
	s_movk_i32 s11, 0x7fff
	v_mov_b32_e32 v27, v112
	v_readlane_b32 s12, v245, 14
	v_readlane_b32 s13, v245, 15
	v_readlane_b32 s14, v245, 16
	v_readlane_b32 s15, v245, 17
	v_readlane_b32 s16, v245, 18
	v_readlane_b32 s17, v245, 19
	v_readlane_b32 s18, v245, 20
	v_readlane_b32 s19, v245, 21
	v_readlane_b32 s20, v245, 22
	v_readlane_b32 s21, v245, 23
	v_readlane_b32 s22, v245, 24
	v_readlane_b32 s23, v245, 25
	global_load_dwordx4 v[28:31], v[18:19], off offset:-3072 nt
	global_load_dwordx4 v[32:35], v[18:19], off offset:-2048 nt
	global_load_dwordx4 v[36:39], v[18:19], off offset:-1024 nt
	global_load_dwordx4 v[40:43], v[18:19], off nt
	v_lshl_add_u64 v[18:19], v[18:19], 0, s[6:7]
	s_waitcnt vmcnt(0)

; __device__ __forceinline__ u32x2 pack4(f32x4 v) { u32x2 r; r.x = cvt_pk_bf16(v[0], v[1]); r.y = cvt_pk_bf16(v[2], v[3]); return r; }
; __device__ __forceinline__ void rmsnorm_phase(const float* x, const float* g, bf16_t* outb, float* outf) {
;     ...
;         for (int i = 0; i < 4; ++i) { v[i] = __builtin_nontemporal_load((const f32x4*)(xr + (lane + i * 64) * 4)); ss += v[i][0] * v[i][0] + v[i][1] * v[i][1] + v[i][2] * v[i][2] + v[i][3] * v[i][3]; }
; #pragma unroll
;         for (int o = 32; o >= 1; o >>= 1) ss += __shfl_xor(ss, o);
;         const float r = rsqrtf(ss * (1.0f / D) + EPS);
; #pragma unroll
;         for (int i = 0; i < 4; ++i) {
;             const f32x4 y = v[i] * r * gv[i];
;             if (outb) *(u32x2*)(outb + (size_t)row * D + (lane + i * 64) * 4) = pack4(y);
;             else __builtin_nontemporal_store(y, (f32x4*)(outf + (size_t)row * D + (lane + i * 64) * 4));
;         }
.Lrp_skip_2:
	v_mov_b32_e32 v46, v29
	v_mov_b32_e32 v47, v33
	v_mov_b32_e32 v44, v28
	v_mov_b32_e32 v45, v32
	v_mov_b32_e32 v54, v37
	v_mov_b32_e32 v55, v41
	v_pk_mul_f32 v[46:47], v[46:47], v[46:47]
	v_mov_b32_e32 v48, v30
	v_mov_b32_e32 v49, v34
	v_mov_b32_e32 v52, v36
	v_mov_b32_e32 v53, v40
	v_pk_mul_f32 v[54:55], v[54:55], v[54:55]
	v_pk_fma_f32 v[44:45], v[44:45], v[44:45], v[46:47]
	v_mov_b32_e32 v50, v31
	v_mov_b32_e32 v51, v35
	v_mov_b32_e32 v56, v38
	v_mov_b32_e32 v57, v42
	v_pk_fma_f32 v[46:47], v[52:53], v[52:53], v[54:55]
	v_pk_fma_f32 v[44:45], v[48:49], v[48:49], v[44:45]
	v_mov_b32_e32 v58, v39
	v_mov_b32_e32 v59, v43
	v_pk_fma_f32 v[46:47], v[56:57], v[56:57], v[46:47]
	v_pk_fma_f32 v[44:45], v[50:51], v[50:51], v[44:45]
	v_pk_fma_f32 v[46:47], v[58:59], v[58:59], v[46:47]
	v_add_f32_e32 v44, v44, v45
	v_add_f32_e32 v44, v44, v46
	v_add_f32_e32 v44, v44, v47
	v_mov_b32_e32 v45, v44
	s_nop 1
	v_permlane32_swap_b32_e32 v44, v45
	v_add_f32_e32 v44, v44, v45
	v_mov_b32_e32 v45, v44
	s_nop 1
	v_permlane16_swap_b32_e32 v44, v45
	v_add_f32_e32 v44, v44, v45
	s_nop 1
	v_add_f32_dpp v44, v44, v44 row_ror:8 row_mask:0xf bank_mask:0xf
	s_nop 1
	v_add_f32_dpp v44, v44, v44 row_ror:4 row_mask:0xf bank_mask:0xf
	s_nop 1
	v_add_f32_dpp v44, v44, v44 quad_perm:[2,3,0,1] row_mask:0xf bank_mask:0xf
	s_nop 1
	v_add_f32_dpp v44, v44, v44 quad_perm:[1,0,3,2] row_mask:0xf bank_mask:0xf
	v_fmamk_f32 v44, v44, 0x3a800000, v26
	v_mul_f32_e32 v45, 0x4b800000, v44
	v_cmp_gt_f32_e32 vcc, s10, v44
	s_nop 1
	v_cndmask_b32_e32 v44, v44, v45, vcc
	v_rsq_f32_e32 v44, v44
	s_nop 0
	v_mul_f32_e32 v45, 0x45800000, v44
	v_cndmask_b32_e32 v44, v44, v45, vcc
	v_pk_mul_f32 v[28:29], v[28:29], v[44:45] op_sel_hi:[1,0]
	v_pk_mul_f32 v[30:31], v[30:31], v[44:45] op_sel_hi:[1,0]
	v_pk_mul_f32 v[32:33], v[32:33], v[44:45] op_sel_hi:[1,0]
	v_pk_mul_f32 v[34:35], v[34:35], v[44:45] op_sel_hi:[1,0]
	v_pk_mul_f32 v[36:37], v[36:37], v[44:45] op_sel_hi:[1,0]
	v_pk_mul_f32 v[38:39], v[38:39], v[44:45] op_sel_hi:[1,0]
	v_pk_mul_f32 v[40:41], v[40:41], v[44:45] op_sel_hi:[1,0]
	v_pk_mul_f32 v[42:43], v[42:43], v[44:45] op_sel_hi:[1,0]
	v_pk_mul_f32 v[30:31], v[10:11], v[30:31]
	v_pk_mul_f32 v[28:29], v[8:9], v[28:29]
	v_pk_mul_f32 v[34:35], v[2:3], v[34:35]
	v_pk_mul_f32 v[32:33], v[0:1], v[32:33]
	v_pk_mul_f32 v[38:39], v[6:7], v[38:39]
	v_pk_mul_f32 v[36:37], v[4:5], v[36:37]
	v_pk_mul_f32 v[42:43], v[14:15], v[42:43]
	v_pk_mul_f32 v[40:41], v[12:13], v[40:41]
	v_cvt_pk_bf16_f32 v28, v28, v29
	v_cvt_pk_bf16_f32 v29, v30, v31
	v_cvt_pk_bf16_f32 v30, v32, v33
	v_cvt_pk_bf16_f32 v31, v34, v35
	v_cvt_pk_bf16_f32 v32, v36, v37
	v_cvt_pk_bf16_f32 v33, v38, v39
	v_cvt_pk_bf16_f32 v34, v40, v41
	v_cvt_pk_bf16_f32 v35, v42, v43
	global_store_dwordx2 v[16:17], v[28:29], off
	global_store_dwordx2 v[16:17], v[30:31], off offset:512
	global_store_dwordx2 v[16:17], v[32:33], off offset:1024
	global_store_dwordx2 v[16:17], v[34:35], off offset:1536
	v_lshl_add_u64 v[16:17], v[16:17], 0, s[2:3]
	s_waitcnt vmcnt(4)
	v_mov_b32_e32 v28, v180
	v_mov_b32_e32 v29, v181
	v_mov_b32_e32 v30, v182
	v_mov_b32_e32 v31, v183
	v_mov_b32_e32 v32, v184
	v_mov_b32_e32 v33, v185
	v_mov_b32_e32 v34, v186
	v_mov_b32_e32 v35, v187
	v_mov_b32_e32 v36, v188
	v_mov_b32_e32 v37, v189
	v_mov_b32_e32 v38, v190
	v_mov_b32_e32 v39, v191
	v_mov_b32_e32 v40, v192
	v_mov_b32_e32 v41, v193
	v_mov_b32_e32 v42, v194
	v_mov_b32_e32 v43, v195
	s_andn2_b64 exec, exec, s[8:9]
	s_cbranch_execnz .LBB0_669

; __device__ __forceinline__ u32x2 pack4(f32x4 v) { u32x2 r; r.x = cvt_pk_bf16(v[0], v[1]); r.y = cvt_pk_bf16(v[2], v[3]); return r; }
; __device__ __forceinline__ void rmsnorm_phase(const float* x, const float* g, bf16_t* outb, float* outf) {
;     ...
;     f32x4 gv[4];
; #pragma unroll
;     for (int i = 0; i < 4; ++i) gv[i] = *(const f32x4*)(g + (lane + i * 64) * 4);
;     for (int row = gw; row < T; row += nw) {
;         const float* xr = x + (size_t)row * D;
;         f32x4 v[4];
;         float ss = 0.f;
; #pragma unroll
;         for (int i = 0; i < 4; ++i) { v[i] = __builtin_nontemporal_load((const f32x4*)(xr + (lane + i * 64) * 4)); ss += v[i][0] * v[i][0] + v[i][1] * v[i][1] + v[i][2] * v[i][2] + v[i][3] * v[i][3]; }
; #pragma unroll
;         for (int o = 32; o >= 1; o >>= 1) ss += __shfl_xor(ss, o);
;         const float r = rsqrtf(ss * (1.0f / D) + EPS);
; #pragma unroll
;         for (int i = 0; i < 4; ++i) {
;             const f32x4 y = v[i] * r * gv[i];
;             if (outb) *(u32x2*)(outb + (size_t)row * D + (lane + i * 64) * 4) = pack4(y);
;             else __builtin_nontemporal_store(y, (f32x4*)(outf + (size_t)row * D + (lane + i * 64) * 4));
;         }
;     }
.LBB0_943:
	s_or_b64 exec, exec, s[34:35]
	s_waitcnt lgkmcnt(0)
	s_barrier
	s_mov_b64 s[0:1], exec
	v_readlane_b32 s2, v245, 49
	v_readlane_b32 s3, v245, 50
	s_and_b64 s[2:3], s[0:1], s[2:3]
	s_mov_b64 exec, s[2:3]
	s_cbranch_execz .LBB0_946
	v_readlane_b32 s8, v245, 10
	v_readlane_b32 s9, v245, 11
	v_readlane_b32 s12, v245, 14
	v_readlane_b32 s13, v245, 15
	s_mov_b64 s[8:9], s[12:13]
	s_add_u32 s2, s8, 0x1000
	s_addc_u32 s3, s9, 0
	global_load_dwordx4 v[0:3], v168, s[2:3]
	global_load_dwordx4 v[4:7], v167, s[2:3]
	global_load_dwordx4 v[8:11], v146, s[2:3]
	global_load_dwordx4 v[12:15], v169, s[2:3]
	v_lshlrev_b64 v[16:17], 11, v[112:113]
	v_lshlrev_b64 v[18:19], 12, v[112:113]
	v_lshl_or_b32 v16, v115, 3, v16
	v_lshl_or_b32 v18, v115, 4, v18
	v_readlane_b32 s10, v245, 12
	v_readlane_b32 s11, v245, 13
	v_lshl_add_u64 v[16:17], s[56:57], 0, v[16:17]
	s_mov_b64 s[2:3], 0x3800000
	s_ashr_i32 s41, s40, 31
	v_lshl_add_u64 v[18:19], s[54:55], 0, v[18:19]
	s_mov_b64 s[6:7], 0xc00
	v_lshl_add_u64 v[16:17], v[16:17], 0, s[2:3]
	s_lshl_b64 s[2:3], s[40:41], 11
	v_lshl_add_u64 v[18:19], v[18:19], 0, s[6:7]
	s_lshl_b64 s[6:7], s[40:41], 12
	s_mov_b64 s[8:9], 0
	v_mov_b32_e32 v20, 0x358637bd
	s_mov_b32 s10, 0x800000
	s_movk_i32 s11, 0x7fff
	v_mov_b32_e32 v21, v112
	v_readlane_b32 s14, v245, 16
	v_readlane_b32 s15, v245, 17
	v_readlane_b32 s16, v245, 18
	v_readlane_b32 s17, v245, 19
	v_readlane_b32 s18, v245, 20
	v_readlane_b32 s19, v245, 21
	v_readlane_b32 s20, v245, 22
	v_readlane_b32 s21, v245, 23
	v_readlane_b32 s22, v245, 24
	v_readlane_b32 s23, v245, 25
	global_load_dwordx4 v[22:25], v[18:19], off offset:-3072 nt
	global_load_dwordx4 v[26:29], v[18:19], off offset:-2048 nt
	global_load_dwordx4 v[30:33], v[18:19], off offset:-1024 nt
	global_load_dwordx4 v[34:37], v[18:19], off nt
	v_lshl_add_u64 v[18:19], v[18:19], 0, s[6:7]
	s_waitcnt vmcnt(0)
.LBB0_945:
	v_add_u32_e32 v21, s40, v21
	v_cmp_lt_i32_e32 vcc, s11, v21
	s_or_b64 s[8:9], vcc, s[8:9]
	s_cbranch_vccnz .Lrp_skip_3
	global_load_dwordx4 v[180:183], v[18:19], off offset:-3072 nt
	global_load_dwordx4 v[184:187], v[18:19], off offset:-2048 nt
	global_load_dwordx4 v[188:191], v[18:19], off offset:-1024 nt
	global_load_dwordx4 v[192:195], v[18:19], off nt
	v_lshl_add_u64 v[18:19], v[18:19], 0, s[6:7]
.Lrp_skip_3:
	v_mov_b32_e32 v40, v23
	v_mov_b32_e32 v41, v27
	v_mov_b32_e32 v38, v22
	v_mov_b32_e32 v39, v26
	v_mov_b32_e32 v48, v31
	v_mov_b32_e32 v49, v35
	v_pk_mul_f32 v[40:41], v[40:41], v[40:41]
	v_mov_b32_e32 v42, v24
	v_mov_b32_e32 v43, v28
	v_mov_b32_e32 v46, v30
	v_mov_b32_e32 v47, v34
	v_pk_mul_f32 v[48:49], v[48:49], v[48:49]
	v_pk_fma_f32 v[38:39], v[38:39], v[38:39], v[40:41]
	v_mov_b32_e32 v44, v25
	v_mov_b32_e32 v45, v29
	v_mov_b32_e32 v50, v32
	v_mov_b32_e32 v51, v36
	v_pk_fma_f32 v[40:41], v[46:47], v[46:47], v[48:49]
	v_pk_fma_f32 v[38:39], v[42:43], v[42:43], v[38:39]
	v_mov_b32_e32 v52, v33
	v_mov_b32_e32 v53, v37
	v_pk_fma_f32 v[40:41], v[50:51], v[50:51], v[40:41]
	v_pk_fma_f32 v[38:39], v[44:45], v[44:45], v[38:39]
	v_pk_fma_f32 v[40:41], v[52:53], v[52:53], v[40:41]
	v_add_f32_e32 v38, v38, v39
	v_add_f32_e32 v38, v38, v40
	v_add_f32_e32 v38, v38, v41
	v_mov_b32_e32 v39, v38
	s_nop 1
	v_permlane32_swap_b32_e32 v38, v39
	v_add_f32_e32 v38, v38, v39
	v_mov_b32_e32 v39, v38
	s_nop 1
	v_permlane16_swap_b32_e32 v38, v39
	v_add_f32_e32 v38, v38, v39
	s_nop 1
	v_add_f32_dpp v38, v38, v38 row_ror:8 row_mask:0xf bank_mask:0xf
	s_nop 1
	v_add_f32_dpp v38, v38, v38 row_ror:4 row_mask:0xf bank_mask:0xf
	s_nop 1
	v_add_f32_dpp v38, v38, v38 quad_perm:[2,3,0,1] row_mask:0xf bank_mask:0xf
	s_nop 1
	v_add_f32_dpp v38, v38, v38 quad_perm:[1,0,3,2] row_mask:0xf bank_mask:0xf
	v_fmamk_f32 v38, v38, 0x3a800000, v20
	v_mul_f32_e32 v39, 0x4b800000, v38
	v_cmp_gt_f32_e32 vcc, s10, v38
	s_nop 1
	v_cndmask_b32_e32 v38, v38, v39, vcc
	v_rsq_f32_e32 v38, v38
	s_nop 0
	v_mul_f32_e32 v39, 0x45800000, v38
	v_cndmask_b32_e32 v38, v38, v39, vcc
	v_pk_mul_f32 v[22:23], v[22:23], v[38:39] op_sel_hi:[1,0]
	v_pk_mul_f32 v[24:25], v[24:25], v[38:39] op_sel_hi:[1,0]
	v_pk_mul_f32 v[26:27], v[26:27], v[38:39] op_sel_hi:[1,0]
	v_pk_mul_f32 v[28:29], v[28:29], v[38:39] op_sel_hi:[1,0]
	v_pk_mul_f32 v[30:31], v[30:31], v[38:39] op_sel_hi:[1,0]
	v_pk_mul_f32 v[32:33], v[32:33], v[38:39] op_sel_hi:[1,0]
	v_pk_mul_f32 v[34:35], v[34:35], v[38:39] op_sel_hi:[1,0]
	v_pk_mul_f32 v[36:37], v[36:37], v[38:39] op_sel_hi:[1,0]
	v_pk_mul_f32 v[24:25], v[10:11], v[24:25]
	v_pk_mul_f32 v[22:23], v[8:9], v[22:23]
	v_pk_mul_f32 v[28:29], v[2:3], v[28:29]
	v_pk_mul_f32 v[26:27], v[0:1], v[26:27]
	v_pk_mul_f32 v[32:33], v[6:7], v[32:33]
	v_pk_mul_f32 v[30:31], v[4:5], v[30:31]
	v_pk_mul_f32 v[36:37], v[14:15], v[36:37]
	v_pk_mul_f32 v[34:35], v[12:13], v[34:35]
	v_cvt_pk_bf16_f32 v22, v22, v23
	v_cvt_pk_bf16_f32 v23, v24, v25
	v_cvt_pk_bf16_f32 v24, v26, v27
	v_cvt_pk_bf16_f32 v25, v28, v29
	v_cvt_pk_bf16_f32 v26, v30, v31
	v_cvt_pk_bf16_f32 v27, v32, v33
	v_cvt_pk_bf16_f32 v28, v34, v35
	v_cvt_pk_bf16_f32 v29, v36, v37
	global_store_dwordx2 v[16:17], v[22:23], off
	global_store_dwordx2 v[16:17], v[24:25], off offset:512
	global_store_dwordx2 v[16:17], v[26:27], off offset:1024
	global_store_dwordx2 v[16:17], v[28:29], off offset:1536
	v_lshl_add_u64 v[16:17], v[16:17], 0, s[2:3]
	s_waitcnt vmcnt(4)
	v_mov_b32_e32 v22, v180
	v_mov_b32_e32 v23, v181
	v_mov_b32_e32 v24, v182
	v_mov_b32_e32 v25, v183
	v_mov_b32_e32 v26, v184
	v_mov_b32_e32 v27, v185
	v_mov_b32_e32 v28, v186
	v_mov_b32_e32 v29, v187
	v_mov_b32_e32 v30, v188
	v_mov_b32_e32 v31, v189
	v_mov_b32_e32 v32, v190
	v_mov_b32_e32 v33, v191
	v_mov_b32_e32 v34, v192
	v_mov_b32_e32 v35, v193
	v_mov_b32_e32 v36, v194
	v_mov_b32_e32 v37, v195
	s_andn2_b64 exec, exec, s[8:9]
	s_cbranch_execnz .LBB0_945

; __device__ __forceinline__ u32x2 pack4(f32x4 v) { u32x2 r; r.x = cvt_pk_bf16(v[0], v[1]); r.y = cvt_pk_bf16(v[2], v[3]); return r; }
; __device__ __forceinline__ void rmsnorm_phase(const float* x, const float* g, bf16_t* outb, float* outf) {
;     ...
;     f32x4 gv[4];
; #pragma unroll
;     for (int i = 0; i < 4; ++i) gv[i] = *(const f32x4*)(g + (lane + i * 64) * 4);
;     for (int row = gw; row < T; row += nw) {
;         const float* xr = x + (size_t)row * D;
;         f32x4 v[4];
;         float ss = 0.f;
; #pragma unroll
;         for (int i = 0; i < 4; ++i) { v[i] = __builtin_nontemporal_load((const f32x4*)(xr + (lane + i * 64) * 4)); ss += v[i][0] * v[i][0] + v[i][1] * v[i][1] + v[i][2] * v[i][2] + v[i][3] * v[i][3]; }
; #pragma unroll
;         for (int o = 32; o >= 1; o >>= 1) ss += __shfl_xor(ss, o);
;         const float r = rsqrtf(ss * (1.0f / D) + EPS);
; #pragma unroll
;         for (int i = 0; i < 4; ++i) {
;             const f32x4 y = v[i] * r * gv[i];
;             if (outb) *(u32x2*)(outb + (size_t)row * D + (lane + i * 64) * 4) = pack4(y);
;             else __builtin_nontemporal_store(y, (f32x4*)(outf + (size_t)row * D + (lane + i * 64) * 4));
;         }
;     }
.LBB0_1102:
	s_or_b64 exec, exec, s[30:31]
	v_readlane_b32 s2, v245, 49
	v_readlane_b32 s3, v245, 50
	s_waitcnt lgkmcnt(0)
	s_barrier
	s_and_saveexec_b64 s[0:1], s[2:3]
	s_cbranch_execz .LBB0_1105
	global_load_dwordx4 v[0:3], v146, s[52:53]
	global_load_dwordx4 v[4:7], v146, s[52:53] offset:1024
	global_load_dwordx4 v[8:11], v146, s[52:53] offset:2048
	global_load_dwordx4 v[12:15], v146, s[52:53] offset:3072
	v_lshlrev_b64 v[16:17], 12, v[112:113]
	v_lshl_or_b32 v16, v115, 4, v16
	v_lshl_add_u64 v[16:17], s[54:55], 0, v[16:17]
	s_mov_b64 s[0:1], 0xc00
	s_ashr_i32 s41, s40, 31
	v_lshl_add_u64 v[16:17], v[16:17], 0, s[0:1]
	s_lshl_b64 s[2:3], s[40:41], 12
	s_mov_b64 s[4:5], 0
	v_mov_b32_e32 v18, 0x358637bd
	s_mov_b32 s6, 0x800000
	s_movk_i32 s7, 0x7fff
	global_load_dwordx4 v[20:23], v[16:17], off offset:-3072 nt
	global_load_dwordx4 v[24:27], v[16:17], off offset:-2048 nt
	global_load_dwordx4 v[28:31], v[16:17], off offset:-1024 nt
	global_load_dwordx4 v[32:35], v[16:17], off nt
	s_waitcnt vmcnt(0)
.LBB0_1104:
	v_add_u32_e32 v112, s40, v112
	v_cmp_lt_i32_e64 s[0:1], s7, v112
	s_or_b64 s[4:5], s[0:1], s[4:5]
	s_cmp_lg_u64 s[0:1], 0
	s_cbranch_scc1 .Lrp_skip_4
	v_lshl_add_u64 v[196:197], v[16:17], 0, s[2:3]
	global_load_dwordx4 v[180:183], v[196:197], off offset:-3072 nt
	global_load_dwordx4 v[184:187], v[196:197], off offset:-2048 nt
	global_load_dwordx4 v[188:191], v[196:197], off offset:-1024 nt
	global_load_dwordx4 v[192:195], v[196:197], off nt
.Lrp_skip_4:
	v_mov_b32_e32 v38, v21
	v_mov_b32_e32 v39, v25
	v_mov_b32_e32 v36, v20
	v_mov_b32_e32 v37, v24
	v_mov_b32_e32 v46, v29
	v_mov_b32_e32 v47, v33
	v_pk_mul_f32 v[38:39], v[38:39], v[38:39]
	v_mov_b32_e32 v40, v22
	v_mov_b32_e32 v41, v26
	v_mov_b32_e32 v44, v28
	v_mov_b32_e32 v45, v32
	v_pk_mul_f32 v[46:47], v[46:47], v[46:47]
	v_pk_fma_f32 v[36:37], v[36:37], v[36:37], v[38:39]
	v_mov_b32_e32 v42, v23
	v_mov_b32_e32 v43, v27
	v_mov_b32_e32 v48, v30
	v_mov_b32_e32 v49, v34
	v_pk_fma_f32 v[38:39], v[44:45], v[44:45], v[46:47]
	v_pk_fma_f32 v[36:37], v[40:41], v[40:41], v[36:37]
	v_mov_b32_e32 v50, v31
	v_mov_b32_e32 v51, v35
	v_pk_fma_f32 v[38:39], v[48:49], v[48:49], v[38:39]
	v_pk_fma_f32 v[36:37], v[42:43], v[42:43], v[36:37]
	v_pk_fma_f32 v[38:39], v[50:51], v[50:51], v[38:39]
	v_add_f32_e32 v19, v36, v37
	v_add_f32_e32 v19, v19, v38
	v_add_f32_e32 v19, v19, v39
	v_mov_b32_e32 v36, v19
	s_nop 1
	v_permlane32_swap_b32_e32 v19, v36
	v_add_f32_e32 v19, v19, v36
	v_mov_b32_e32 v36, v19
	s_nop 1
	v_permlane16_swap_b32_e32 v19, v36
	v_add_f32_e32 v19, v19, v36
	s_nop 1
	v_add_f32_dpp v19, v19, v19 row_ror:8 row_mask:0xf bank_mask:0xf
	s_nop 1
	v_add_f32_dpp v19, v19, v19 row_ror:4 row_mask:0xf bank_mask:0xf
	s_nop 1
	v_add_f32_dpp v19, v19, v19 quad_perm:[2,3,0,1] row_mask:0xf bank_mask:0xf
	s_nop 1
	v_add_f32_dpp v19, v19, v19 quad_perm:[1,0,3,2] row_mask:0xf bank_mask:0xf
	v_fmamk_f32 v19, v19, 0x3a800000, v18
	v_mul_f32_e32 v36, 0x4b800000, v19
	v_cmp_gt_f32_e32 vcc, s6, v19
	s_nop 1
	v_cndmask_b32_e32 v19, v19, v36, vcc
	v_rsq_f32_e32 v19, v19
	s_nop 0
	v_mul_f32_e32 v36, 0x45800000, v19
	v_cndmask_b32_e32 v36, v19, v36, vcc
	v_pk_mul_f32 v[20:21], v[20:21], v[36:37] op_sel_hi:[1,0]
	v_pk_mul_f32 v[22:23], v[22:23], v[36:37] op_sel_hi:[1,0]
	v_pk_mul_f32 v[24:25], v[24:25], v[36:37] op_sel_hi:[1,0]
	v_pk_mul_f32 v[26:27], v[26:27], v[36:37] op_sel_hi:[1,0]
	v_pk_mul_f32 v[28:29], v[28:29], v[36:37] op_sel_hi:[1,0]
	v_pk_mul_f32 v[30:31], v[30:31], v[36:37] op_sel_hi:[1,0]
	v_pk_mul_f32 v[32:33], v[32:33], v[36:37] op_sel_hi:[1,0]
	v_pk_mul_f32 v[34:35], v[34:35], v[36:37] op_sel_hi:[1,0]
	v_pk_mul_f32 v[22:23], v[2:3], v[22:23]
	v_pk_mul_f32 v[20:21], v[0:1], v[20:21]
	v_pk_mul_f32 v[26:27], v[6:7], v[26:27]
	v_pk_mul_f32 v[24:25], v[4:5], v[24:25]
	v_pk_mul_f32 v[30:31], v[10:11], v[30:31]
	v_pk_mul_f32 v[28:29], v[8:9], v[28:29]
	v_pk_mul_f32 v[34:35], v[14:15], v[34:35]
	v_pk_mul_f32 v[32:33], v[12:13], v[32:33]
	global_store_dwordx4 v[16:17], v[20:23], off offset:-3072 nt
	global_store_dwordx4 v[16:17], v[24:27], off offset:-2048 nt
	global_store_dwordx4 v[16:17], v[28:31], off offset:-1024 nt
	global_store_dwordx4 v[16:17], v[32:35], off nt
	v_lshl_add_u64 v[16:17], v[16:17], 0, s[2:3]
	s_waitcnt vmcnt(4)
	v_mov_b32_e32 v20, v180
	v_mov_b32_e32 v21, v181
	v_mov_b32_e32 v22, v182
	v_mov_b32_e32 v23, v183
	v_mov_b32_e32 v24, v184
	v_mov_b32_e32 v25, v185
	v_mov_b32_e32 v26, v186
	v_mov_b32_e32 v27, v187
	v_mov_b32_e32 v28, v188
	v_mov_b32_e32 v29, v189
	v_mov_b32_e32 v30, v190
	v_mov_b32_e32 v31, v191
	v_mov_b32_e32 v32, v192
	v_mov_b32_e32 v33, v193
	v_mov_b32_e32 v34, v194
	v_mov_b32_e32 v35, v195
	s_andn2_b64 exec, exec, s[4:5]
	s_cbranch_execnz .LBB0_1104
